# EpiIn: 8 serialized SS loads issued together, one wait
# baseline (speedup 1.0000x reference)
; __device__ __forceinline__ unsigned cvt_pk_bf16(float lo, float hi) { unsigned r; asm volatile("v_cvt_pk_bf16_f32 %0, %1, %2" : "=v"(r) : "v"(lo), "v"(hi)); return r; }
; #define EPI_ST(p, v) __builtin_nontemporal_store((v), (p))
;     __device__ __forceinline__ void operator()(const f32x4 (&acc)[2][2][4][2], const pg8::Unit& u, int wr, int wc, int fr, int fq) const {
;     ...
;         const int row0 = u.pm * 256 + wr * 64 + fr;
;         float rs[2][4];
; #pragma unroll
;         for (int ai = 0; ai < 2; ++ai)
; #pragma unroll
;             for (int m = 0; m < 4; ++m) rs[ai][m] = rsqrtf(SS[row0 + ai * 128 + m * 16] * (1.f / DM) + EPS);
;     ...
; #pragma unroll
;             for (int ai = 0; ai < 2; ++ai)
; #pragma unroll
;                 for (int m = 0; m < 4; ++m) { bf16_t* rp = PR + (size_t)(row0 + ai * 128 + m * 16) * PRW + (u.pn - 8) * 256 + wc * 32 + 8 * fq; const float r1 = rs[ai][m];
; #pragma unroll
;                     for (int bj = 0; bj < 2; ++bj) { const f32x4 v0 = acc[ai][bj][m][0] * r1, v1 = acc[ai][bj][m][1] * r1; u32x4 w;
;                         w.x = cvt_pk_bf16(v0[0], v0[1]); w.y = cvt_pk_bf16(v0[2], v0[3]); w.z = cvt_pk_bf16(v1[0], v1[1]); w.w = cvt_pk_bf16(v1[2], v1[3]);
;                         EPI_ST((u32x4*)(rp + bj * 128), w); } }
.LBB0_257:
	v_mov_b32_e32 v155, v149
	s_mov_b32 s8, s67
	v_mov_b32_e32 v162, v147
	s_mov_b32 s6, s62
	s_lshl_b32 s7, s52, 8
	s_lshl_b32 s9, s6, 6
	s_add_i32 s6, s9, s7
	v_add_u32_e32 v144, s6, v162
	v_ashrrev_i32_e32 v145, 31, v144
	v_lshl_add_u64 v[128:129], v[144:145], 2, s[28:29]
	global_load_dword v146, v[128:129], off
	global_load_dword v148, v[128:129], off offset:64
	global_load_dword v150, v[128:129], off offset:128
	global_load_dword v152, v[128:129], off offset:192
	global_load_dword v154, v[128:129], off offset:512
	global_load_dword v156, v[128:129], off offset:576
	global_load_dword v158, v[128:129], off offset:640
	global_load_dword v160, v[128:129], off offset:704
	v_readlane_b32 s80, v244, 15
	v_readlane_b32 s81, v244, 16
	v_readlane_b32 s83, v244, 18
	v_readlane_b32 s80, v244, 21
	s_mov_b64 s[30:31], -1
	s_cmp_lg_u32 s44, 24
	v_readlane_b32 s82, v244, 17
	v_readlane_b32 s81, v244, 22
	v_readlane_b32 s83, v244, 23
	s_waitcnt vmcnt(0)
	v_fmamk_f32 v146, v146, 0x3a000000, v212
	v_cmp_gt_f32_e32 vcc, s14, v146
	v_mul_f32_e32 v131, 0x4b800000, v146
	s_nop 0
	v_cndmask_b32_e32 v146, v146, v131, vcc
	v_rsq_f32_e32 v146, v146
	s_nop 0
	v_mul_f32_e32 v131, 0x45800000, v146
	v_cndmask_b32_e32 v146, v146, v131, vcc
	v_fmamk_f32 v148, v148, 0x3a000000, v212
	v_cmp_gt_f32_e32 vcc, s14, v148
	v_mul_f32_e32 v131, 0x4b800000, v148
	s_nop 0
	v_cndmask_b32_e32 v148, v148, v131, vcc
	v_rsq_f32_e32 v148, v148
	s_nop 0
	v_mul_f32_e32 v131, 0x45800000, v148
	v_cndmask_b32_e32 v148, v148, v131, vcc
	v_fmamk_f32 v150, v150, 0x3a000000, v212
	v_cmp_gt_f32_e32 vcc, s14, v150
	v_mul_f32_e32 v131, 0x4b800000, v150
	s_nop 0
	v_cndmask_b32_e32 v150, v150, v131, vcc
	v_rsq_f32_e32 v150, v150
	s_nop 0
	v_mul_f32_e32 v131, 0x45800000, v150
	v_cndmask_b32_e32 v150, v150, v131, vcc
	v_fmamk_f32 v152, v152, 0x3a000000, v212
	v_cmp_gt_f32_e32 vcc, s14, v152
	v_mul_f32_e32 v131, 0x4b800000, v152
	s_nop 0
	v_cndmask_b32_e32 v152, v152, v131, vcc
	v_rsq_f32_e32 v152, v152
	s_nop 0
	v_mul_f32_e32 v131, 0x45800000, v152
	v_cndmask_b32_e32 v152, v152, v131, vcc
	v_fmamk_f32 v154, v154, 0x3a000000, v212
	v_cmp_gt_f32_e32 vcc, s14, v154
	v_mul_f32_e32 v131, 0x4b800000, v154
	s_nop 0
	v_cndmask_b32_e32 v154, v154, v131, vcc
	v_rsq_f32_e32 v154, v154
	s_nop 0
	v_mul_f32_e32 v131, 0x45800000, v154
	v_cndmask_b32_e32 v154, v154, v131, vcc
	v_fmamk_f32 v156, v156, 0x3a000000, v212
	v_cmp_gt_f32_e32 vcc, s14, v156
	v_mul_f32_e32 v131, 0x4b800000, v156
	s_nop 0
	v_cndmask_b32_e32 v156, v156, v131, vcc
	v_rsq_f32_e32 v156, v156
	s_nop 0
	v_mul_f32_e32 v131, 0x45800000, v156
	v_cndmask_b32_e32 v156, v156, v131, vcc
	v_fmamk_f32 v158, v158, 0x3a000000, v212
	v_cmp_gt_f32_e32 vcc, s14, v158
	v_mul_f32_e32 v131, 0x4b800000, v158
	s_nop 0
	v_cndmask_b32_e32 v158, v158, v131, vcc
	v_rsq_f32_e32 v158, v158
	s_nop 0
	v_mul_f32_e32 v131, 0x45800000, v158
	v_cndmask_b32_e32 v158, v158, v131, vcc
	v_fmamk_f32 v160, v160, 0x3a000000, v212
	v_cmp_gt_f32_e32 vcc, s14, v160
	v_mul_f32_e32 v131, 0x4b800000, v160
	s_nop 0
	v_cndmask_b32_e32 v160, v160, v131, vcc
	v_rsq_f32_e32 v160, v160
	s_nop 0
	v_mul_f32_e32 v131, 0x45800000, v160
	v_cndmask_b32_e32 v160, v160, v131, vcc
	s_cbranch_scc0 .LBB0_286
	s_cmp_lt_i32 s10, 0
	s_mov_b64 s[6:7], -1
	s_cbranch_scc0 .LBB0_280
	v_add_u32_e32 v186, 16, v144
	v_add_u32_e32 v184, 32, v144
	v_add_u32_e32 v182, 48, v144
	v_add_u32_e32 v180, 0x80, v144
	v_add_u32_e32 v178, 0x90, v144
	v_add_u32_e32 v166, 0xa0, v144
	v_add_u32_e32 v164, 0xb0, v144
	s_lshl_b32 s52, s8, 5
	v_ashrrev_i32_e32 v187, 31, v186
	v_ashrrev_i32_e32 v185, 31, v184
	v_ashrrev_i32_e32 v183, 31, v182
	v_ashrrev_i32_e32 v181, 31, v180
	v_ashrrev_i32_e32 v179, 31, v178
	v_ashrrev_i32_e32 v167, 31, v166
	v_ashrrev_i32_e32 v165, 31, v164
	s_cmp_lt_i32 s44, 8
	s_cbranch_scc1 .LBB0_261
	s_lshl_b32 s6, s44, 8
	s_addk_i32 s6, 0xf800
	v_lshlrev_b64 v[130:131], 13, v[144:145]
	s_ashr_i32 s7, s6, 31
	s_ashr_i32 s53, s52, 31
	v_lshlrev_b32_e32 v128, 3, v155
	v_lshl_add_u64 v[130:131], s[2:3], 0, v[130:131]
	s_lshl_b64 s[54:55], s[6:7], 1
	v_ashrrev_i32_e32 v129, 31, v128
	v_lshl_add_u64 v[130:131], v[130:131], 0, s[54:55]
	s_lshl_b64 s[56:57], s[52:53], 1
	v_lshl_add_u64 v[130:131], v[130:131], 0, s[56:57]
	v_lshlrev_b64 v[128:129], 1, v[128:129]
	v_lshl_add_u64 v[134:135], v[130:131], 0, v[128:129]
	v_pk_mul_f32 v[130:131], v[36:37], v[146:147] op_sel_hi:[1,0]
	v_pk_mul_f32 v[132:133], v[38:39], v[146:147] op_sel_hi:[1,0]
	v_cvt_pk_bf16_f32 v130, v130, v131
	v_pk_mul_f32 v[188:189], v[86:87], v[146:147] op_sel_hi:[1,0]
	v_cvt_pk_bf16_f32 v131, v132, v133
	v_pk_mul_f32 v[190:191], v[84:85], v[146:147] op_sel_hi:[1,0]
	s_mov_b64 s[6:7], 0
	v_cvt_pk_bf16_f32 v132, v190, v191
	v_cvt_pk_bf16_f32 v133, v188, v189
	global_store_dwordx4 v[134:135], v[130:133], off
	v_pk_mul_f32 v[188:189], v[70:71], v[146:147] op_sel_hi:[1,0]
	v_pk_mul_f32 v[190:191], v[68:69], v[146:147] op_sel_hi:[1,0]
	v_pk_mul_f32 v[130:131], v[72:73], v[146:147] op_sel_hi:[1,0]
	v_pk_mul_f32 v[132:133], v[74:75], v[146:147] op_sel_hi:[1,0]
	v_cvt_pk_bf16_f32 v130, v130, v131
	s_nop 0
	v_cvt_pk_bf16_f32 v131, v132, v133
	v_cvt_pk_bf16_f32 v132, v190, v191
	v_cvt_pk_bf16_f32 v133, v188, v189
	global_store_dwordx4 v[134:135], v[130:133], off offset:256
	v_pk_mul_f32 v[188:189], v[66:67], v[148:149] op_sel_hi:[1,0]
	v_pk_mul_f32 v[190:191], v[64:65], v[148:149] op_sel_hi:[1,0]
	v_lshlrev_b64 v[130:131], 13, v[186:187]
	v_lshl_add_u64 v[130:131], s[2:3], 0, v[130:131]
	v_lshl_add_u64 v[130:131], v[130:131], 0, s[54:55]
	v_lshl_add_u64 v[130:131], v[130:131], 0, s[56:57]
	v_lshl_add_u64 v[134:135], v[130:131], 0, v[128:129]
; __device__ __forceinline__ unsigned cvt_pk_bf16(float lo, float hi) { unsigned r; asm volatile("v_cvt_pk_bf16_f32 %0, %1, %2" : "=v"(r) : "v"(lo), "v"(hi)); return r; }
; #define EPI_ST(p, v) __builtin_nontemporal_store((v), (p))
;     __device__ __forceinline__ void operator()(const f32x4 (&acc)[2][2][4][2], const pg8::Unit& u, int wr, int wc, int fr, int fq) const {
;     ...
; #pragma unroll
;             for (int ai = 0; ai < 2; ++ai)
; #pragma unroll
;                 for (int m = 0; m < 4; ++m) { bf16_t* rp = PR + (size_t)(row0 + ai * 128 + m * 16) * PRW + (u.pn - 8) * 256 + wc * 32 + 8 * fq; const float r1 = rs[ai][m];
; #pragma unroll
;                     for (int bj = 0; bj < 2; ++bj) { const f32x4 v0 = acc[ai][bj][m][0] * r1, v1 = acc[ai][bj][m][1] * r1; u32x4 w;
;                         w.x = cvt_pk_bf16(v0[0], v0[1]); w.y = cvt_pk_bf16(v0[2], v0[3]); w.z = cvt_pk_bf16(v1[0], v1[1]); w.w = cvt_pk_bf16(v1[2], v1[3]);
;                         EPI_ST((u32x4*)(rp + bj * 128), w); } }
	v_pk_mul_f32 v[130:131], v[28:29], v[148:149] op_sel_hi:[1,0]
	v_pk_mul_f32 v[132:133], v[30:31], v[148:149] op_sel_hi:[1,0]
	v_cvt_pk_bf16_f32 v130, v130, v131
	s_nop 0
	v_cvt_pk_bf16_f32 v131, v132, v133
	v_cvt_pk_bf16_f32 v132, v190, v191
	v_cvt_pk_bf16_f32 v133, v188, v189
	global_store_dwordx4 v[134:135], v[130:133], off
	v_pk_mul_f32 v[188:189], v[58:59], v[148:149] op_sel_hi:[1,0]
	v_pk_mul_f32 v[190:191], v[56:57], v[148:149] op_sel_hi:[1,0]
	v_pk_mul_f32 v[130:131], v[60:61], v[148:149] op_sel_hi:[1,0]
	v_pk_mul_f32 v[132:133], v[62:63], v[148:149] op_sel_hi:[1,0]
	v_cvt_pk_bf16_f32 v130, v130, v131
	s_nop 0
	v_cvt_pk_bf16_f32 v131, v132, v133
	v_cvt_pk_bf16_f32 v132, v190, v191
	v_cvt_pk_bf16_f32 v133, v188, v189
	global_store_dwordx4 v[134:135], v[130:133], off offset:256
	v_pk_mul_f32 v[188:189], v[54:55], v[150:151] op_sel_hi:[1,0]
	v_pk_mul_f32 v[190:191], v[52:53], v[150:151] op_sel_hi:[1,0]
	v_lshlrev_b64 v[130:131], 13, v[184:185]
	v_lshl_add_u64 v[130:131], s[2:3], 0, v[130:131]
	v_lshl_add_u64 v[130:131], v[130:131], 0, s[54:55]
	v_lshl_add_u64 v[130:131], v[130:131], 0, s[56:57]
	v_lshl_add_u64 v[134:135], v[130:131], 0, v[128:129]
	v_pk_mul_f32 v[130:131], v[20:21], v[150:151] op_sel_hi:[1,0]
	v_pk_mul_f32 v[132:133], v[22:23], v[150:151] op_sel_hi:[1,0]
	v_cvt_pk_bf16_f32 v130, v130, v131
	s_nop 0
	v_cvt_pk_bf16_f32 v131, v132, v133
	v_cvt_pk_bf16_f32 v132, v190, v191
	v_cvt_pk_bf16_f32 v133, v188, v189
	global_store_dwordx4 v[134:135], v[130:133], off
	v_pk_mul_f32 v[188:189], v[46:47], v[150:151] op_sel_hi:[1,0]
	v_pk_mul_f32 v[190:191], v[44:45], v[150:151] op_sel_hi:[1,0]
	v_pk_mul_f32 v[130:131], v[48:49], v[150:151] op_sel_hi:[1,0]
	v_pk_mul_f32 v[132:133], v[50:51], v[150:151] op_sel_hi:[1,0]
	v_cvt_pk_bf16_f32 v130, v130, v131
	s_nop 0
	v_cvt_pk_bf16_f32 v131, v132, v133
	v_cvt_pk_bf16_f32 v132, v190, v191
	v_cvt_pk_bf16_f32 v133, v188, v189
	global_store_dwordx4 v[134:135], v[130:133], off offset:256
	v_pk_mul_f32 v[188:189], v[42:43], v[152:153] op_sel_hi:[1,0]
	v_pk_mul_f32 v[190:191], v[40:41], v[152:153] op_sel_hi:[1,0]
	v_lshlrev_b64 v[130:131], 13, v[182:183]
	v_lshl_add_u64 v[130:131], s[2:3], 0, v[130:131]
	v_lshl_add_u64 v[130:131], v[130:131], 0, s[54:55]
	v_lshl_add_u64 v[130:131], v[130:131], 0, s[56:57]
	v_lshl_add_u64 v[134:135], v[130:131], 0, v[128:129]
	v_pk_mul_f32 v[130:131], v[16:17], v[152:153] op_sel_hi:[1,0]
	v_pk_mul_f32 v[132:133], v[18:19], v[152:153] op_sel_hi:[1,0]
	v_cvt_pk_bf16_f32 v130, v130, v131
	s_nop 0
	v_cvt_pk_bf16_f32 v131, v132, v133
	v_cvt_pk_bf16_f32 v132, v190, v191
	v_cvt_pk_bf16_f32 v133, v188, v189
	global_store_dwordx4 v[134:135], v[130:133], off
	v_pk_mul_f32 v[188:189], v[26:27], v[152:153] op_sel_hi:[1,0]
	v_pk_mul_f32 v[190:191], v[24:25], v[152:153] op_sel_hi:[1,0]
	v_pk_mul_f32 v[130:131], v[32:33], v[152:153] op_sel_hi:[1,0]
	v_pk_mul_f32 v[132:133], v[34:35], v[152:153] op_sel_hi:[1,0]
	v_cvt_pk_bf16_f32 v130, v130, v131
	s_nop 0
	v_cvt_pk_bf16_f32 v131, v132, v133
	v_cvt_pk_bf16_f32 v132, v190, v191
	v_cvt_pk_bf16_f32 v133, v188, v189
	global_store_dwordx4 v[134:135], v[130:133], off offset:256
	v_pk_mul_f32 v[188:189], v[126:127], v[154:155] op_sel_hi:[1,0]
	v_pk_mul_f32 v[190:191], v[124:125], v[154:155] op_sel_hi:[1,0]
	v_lshlrev_b64 v[130:131], 13, v[180:181]
	v_lshl_add_u64 v[130:131], s[2:3], 0, v[130:131]
	v_lshl_add_u64 v[130:131], v[130:131], 0, s[54:55]
	v_lshl_add_u64 v[130:131], v[130:131], 0, s[56:57]
	v_lshl_add_u64 v[134:135], v[130:131], 0, v[128:129]
	v_pk_mul_f32 v[130:131], v[12:13], v[154:155] op_sel_hi:[1,0]
	v_pk_mul_f32 v[132:133], v[14:15], v[154:155] op_sel_hi:[1,0]
	v_cvt_pk_bf16_f32 v130, v130, v131
	s_nop 0
	v_cvt_pk_bf16_f32 v131, v132, v133
	v_cvt_pk_bf16_f32 v132, v190, v191
	v_cvt_pk_bf16_f32 v133, v188, v189
	global_store_dwordx4 v[134:135], v[130:133], off
	v_pk_mul_f32 v[188:189], v[118:119], v[154:155] op_sel_hi:[1,0]
; __device__ __forceinline__ unsigned cvt_pk_bf16(float lo, float hi) { unsigned r; asm volatile("v_cvt_pk_bf16_f32 %0, %1, %2" : "=v"(r) : "v"(lo), "v"(hi)); return r; }
; #define EPI_ST(p, v) __builtin_nontemporal_store((v), (p))
;     __device__ __forceinline__ void operator()(const f32x4 (&acc)[2][2][4][2], const pg8::Unit& u, int wr, int wc, int fr, int fq) const {
;     ...
; #pragma unroll
;             for (int ai = 0; ai < 2; ++ai)
; #pragma unroll
;                 for (int m = 0; m < 4; ++m) { bf16_t* rp = PR + (size_t)(row0 + ai * 128 + m * 16) * PRW + (u.pn - 8) * 256 + wc * 32 + 8 * fq; const float r1 = rs[ai][m];
; #pragma unroll
;                     for (int bj = 0; bj < 2; ++bj) { const f32x4 v0 = acc[ai][bj][m][0] * r1, v1 = acc[ai][bj][m][1] * r1; u32x4 w;
;                         w.x = cvt_pk_bf16(v0[0], v0[1]); w.y = cvt_pk_bf16(v0[2], v0[3]); w.z = cvt_pk_bf16(v1[0], v1[1]); w.w = cvt_pk_bf16(v1[2], v1[3]);
;                         EPI_ST((u32x4*)(rp + bj * 128), w); } }
	v_pk_mul_f32 v[190:191], v[116:117], v[154:155] op_sel_hi:[1,0]
	v_pk_mul_f32 v[130:131], v[120:121], v[154:155] op_sel_hi:[1,0]
	v_pk_mul_f32 v[132:133], v[122:123], v[154:155] op_sel_hi:[1,0]
	v_cvt_pk_bf16_f32 v130, v130, v131
	s_nop 0
	v_cvt_pk_bf16_f32 v131, v132, v133
	v_cvt_pk_bf16_f32 v132, v190, v191
	v_cvt_pk_bf16_f32 v133, v188, v189
	global_store_dwordx4 v[134:135], v[130:133], off offset:256
	v_pk_mul_f32 v[188:189], v[114:115], v[156:157] op_sel_hi:[1,0]
	v_pk_mul_f32 v[190:191], v[112:113], v[156:157] op_sel_hi:[1,0]
	v_lshlrev_b64 v[130:131], 13, v[178:179]
	v_lshl_add_u64 v[130:131], s[2:3], 0, v[130:131]
	v_lshl_add_u64 v[130:131], v[130:131], 0, s[54:55]
	v_lshl_add_u64 v[130:131], v[130:131], 0, s[56:57]
	v_lshl_add_u64 v[134:135], v[130:131], 0, v[128:129]
	v_pk_mul_f32 v[130:131], v[8:9], v[156:157] op_sel_hi:[1,0]
	v_pk_mul_f32 v[132:133], v[10:11], v[156:157] op_sel_hi:[1,0]
	v_cvt_pk_bf16_f32 v130, v130, v131
	s_nop 0
	v_cvt_pk_bf16_f32 v131, v132, v133
	v_cvt_pk_bf16_f32 v132, v190, v191
	v_cvt_pk_bf16_f32 v133, v188, v189
	global_store_dwordx4 v[134:135], v[130:133], off
	v_pk_mul_f32 v[188:189], v[106:107], v[156:157] op_sel_hi:[1,0]
	v_pk_mul_f32 v[190:191], v[104:105], v[156:157] op_sel_hi:[1,0]
	v_pk_mul_f32 v[130:131], v[108:109], v[156:157] op_sel_hi:[1,0]
	v_pk_mul_f32 v[132:133], v[110:111], v[156:157] op_sel_hi:[1,0]
	v_cvt_pk_bf16_f32 v130, v130, v131
	s_nop 0
	v_cvt_pk_bf16_f32 v131, v132, v133
	v_cvt_pk_bf16_f32 v132, v190, v191
	v_cvt_pk_bf16_f32 v133, v188, v189
	global_store_dwordx4 v[134:135], v[130:133], off offset:256
	v_pk_mul_f32 v[188:189], v[102:103], v[158:159] op_sel_hi:[1,0]
	v_pk_mul_f32 v[190:191], v[100:101], v[158:159] op_sel_hi:[1,0]
	v_lshlrev_b64 v[130:131], 13, v[166:167]
	v_lshl_add_u64 v[130:131], s[2:3], 0, v[130:131]
	v_lshl_add_u64 v[130:131], v[130:131], 0, s[54:55]
	v_lshl_add_u64 v[130:131], v[130:131], 0, s[56:57]
	v_lshl_add_u64 v[134:135], v[130:131], 0, v[128:129]
	v_pk_mul_f32 v[130:131], v[4:5], v[158:159] op_sel_hi:[1,0]
	v_pk_mul_f32 v[132:133], v[6:7], v[158:159] op_sel_hi:[1,0]
	v_cvt_pk_bf16_f32 v130, v130, v131
	s_nop 0
	v_cvt_pk_bf16_f32 v131, v132, v133
	v_cvt_pk_bf16_f32 v132, v190, v191
	v_cvt_pk_bf16_f32 v133, v188, v189
	global_store_dwordx4 v[134:135], v[130:133], off
	v_pk_mul_f32 v[188:189], v[94:95], v[158:159] op_sel_hi:[1,0]
	v_pk_mul_f32 v[190:191], v[92:93], v[158:159] op_sel_hi:[1,0]
	v_pk_mul_f32 v[130:131], v[96:97], v[158:159] op_sel_hi:[1,0]
	v_pk_mul_f32 v[132:133], v[98:99], v[158:159] op_sel_hi:[1,0]
	v_cvt_pk_bf16_f32 v130, v130, v131
	s_nop 0
	v_cvt_pk_bf16_f32 v131, v132, v133
	v_cvt_pk_bf16_f32 v132, v190, v191
	v_cvt_pk_bf16_f32 v133, v188, v189
	global_store_dwordx4 v[134:135], v[130:133], off offset:256
	v_pk_mul_f32 v[134:135], v[90:91], v[160:161] op_sel_hi:[1,0]
	v_pk_mul_f32 v[188:189], v[88:89], v[160:161] op_sel_hi:[1,0]
	v_lshlrev_b64 v[130:131], 13, v[164:165]
	v_lshl_add_u64 v[130:131], s[2:3], 0, v[130:131]
	v_lshl_add_u64 v[130:131], v[130:131], 0, s[54:55]
	v_lshl_add_u64 v[130:131], v[130:131], 0, s[56:57]
	v_lshl_add_u64 v[132:133], v[130:131], 0, v[128:129]
	v_pk_mul_f32 v[130:131], v[2:3], v[160:161] op_sel_hi:[1,0]
	v_pk_mul_f32 v[128:129], v[0:1], v[160:161] op_sel_hi:[1,0]
	s_nop 0
	v_cvt_pk_bf16_f32 v128, v128, v129
	v_cvt_pk_bf16_f32 v129, v130, v131
	v_cvt_pk_bf16_f32 v130, v188, v189
	v_cvt_pk_bf16_f32 v131, v134, v135
	global_store_dwordx4 v[132:133], v[128:131], off
	v_pk_mul_f32 v[134:135], v[78:79], v[160:161] op_sel_hi:[1,0]
	v_pk_mul_f32 v[188:189], v[76:77], v[160:161] op_sel_hi:[1,0]
	v_pk_mul_f32 v[130:131], v[82:83], v[160:161] op_sel_hi:[1,0]
	v_pk_mul_f32 v[128:129], v[80:81], v[160:161] op_sel_hi:[1,0]
	s_nop 0
	v_cvt_pk_bf16_f32 v128, v128, v129
	v_cvt_pk_bf16_f32 v129, v130, v131
	v_cvt_pk_bf16_f32 v130, v188, v189
	v_cvt_pk_bf16_f32 v131, v134, v135
	global_store_dwordx4 v[132:133], v[128:131], off offset:256
